# MLA softmax: row max over raw scores then one scale (bit-identical); duplicate panel-ready poll removed for 256-row tiles
# speedup vs baseline: 1.0027x; 1.0027x over previous
.LBB0_201:
	flat_load_dword v4, v[0:1] sc1
	s_waitcnt vmcnt(0) lgkmcnt(0)
	v_readfirstlane_b32 s15, v4
	s_cmp_lt_u32 s15, 64
	s_cselect_b64 s[18:19], -1, 0
	s_and_b64 vcc, exec, s[18:19]
	s_cbranch_vccnz .LBB0_203
.LBB0_203:
	s_mov_b64 s[16:17], -1
	s_andn2_b64 vcc, exec, s[18:19]
	s_mov_b64 s[18:19], -1
	s_cbranch_vccnz .LBB0_200
	s_and_b32 s15, s11, 0xff
	s_cmp_lg_u32 s15, 0
	s_cselect_b64 s[18:19], -1, 0
	s_cmp_eq_u32 s15, 0
	s_cbranch_scc1 .LBB0_206
	s_andn2_b64 vcc, exec, s[18:19]
	s_mov_b64 s[18:19], -1
	s_cbranch_vccnz .LBB0_200
	s_branch .LBB0_207

.LBB0_230:
	v_mov_b64_e32 v[144:145], s[46:47]
	s_waitcnt vmcnt(0)
	flat_load_dword v144, v[144:145] sc1
	s_waitcnt vmcnt(0) lgkmcnt(0)
	v_readfirstlane_b32 s56, v144
	s_cmp_lt_u32 s56, 64
	s_cselect_b64 s[58:59], -1, 0
	s_and_b64 vcc, exec, s[58:59]
	s_cbranch_vccnz .LBB0_232
.LBB0_232:
	s_mov_b64 s[56:57], -1
	s_andn2_b64 vcc, exec, s[58:59]
	s_mov_b64 s[58:59], -1
	s_cbranch_vccnz .LBB0_229
	s_and_b32 s56, s26, 0xff
	s_cmp_lg_u32 s56, 0
	s_cselect_b64 s[58:59], -1, 0
	s_cmp_eq_u32 s56, 0
	s_cbranch_scc1 .LBB0_235
	s_mov_b64 s[56:57], -1
	s_andn2_b64 vcc, exec, s[58:59]
	s_mov_b64 s[58:59], -1
	s_cbranch_vccnz .LBB0_229
	s_branch .LBB0_236

.LBB0_1211:
	s_bitcmp1_b32 s10, 0
	s_cselect_b32 s11, 0xb800, 0
	s_setprio 1
	v_or_b32_e32 v80, s11, v94
	v_add_u32_e32 v109, v80, v187
	ds_read_b128 v[220:223], v109
	ds_read_b128 v[224:227], v109 offset:64
	ds_read_b128 v[228:231], v109 offset:3328
	ds_read_b128 v[232:235], v109 offset:6656
	ds_read_b128 v[236:239], v109 offset:9984
	ds_read_b128 v[240:243], v109 offset:3392
	ds_read_b128 v[244:247], v109 offset:6720
	ds_read_b128 v[248:251], v109 offset:10048
	s_waitcnt lgkmcnt(7)
	v_mfma_f32_16x16x32_bf16 v[112:115], v[220:223], v[4:7], v[0:3]
	v_mfma_f32_16x16x32_bf16 v[82:85], v[220:223], v[16:19], v[0:3]
	ds_read_b128 v[220:223], v109 offset:128
	s_waitcnt lgkmcnt(7)
	v_mfma_f32_16x16x32_bf16 v[112:115], v[224:227], v[8:11], v[112:115]
	v_mfma_f32_16x16x32_bf16 v[82:85], v[224:227], v[20:23], v[82:85]
	ds_read_b128 v[224:227], v109 offset:3456
	s_waitcnt lgkmcnt(7)
	v_mfma_f32_16x16x32_bf16 v[120:123], v[228:231], v[4:7], v[0:3]
	v_mfma_f32_16x16x32_bf16 v[116:119], v[228:231], v[16:19], v[0:3]
	ds_read_b128 v[228:231], v109 offset:6784
	s_waitcnt lgkmcnt(5)
	v_mfma_f32_16x16x32_bf16 v[120:123], v[240:243], v[8:11], v[120:123]
	v_mfma_f32_16x16x32_bf16 v[116:119], v[240:243], v[20:23], v[116:119]
	ds_read_b128 v[240:243], v109 offset:10112
	v_mfma_f32_16x16x32_bf16 v[128:131], v[232:235], v[4:7], v[0:3]
	v_mfma_f32_16x16x32_bf16 v[124:127], v[232:235], v[16:19], v[0:3]
	s_waitcnt lgkmcnt(5)
	v_mfma_f32_16x16x32_bf16 v[128:131], v[244:247], v[8:11], v[128:131]
	v_mfma_f32_16x16x32_bf16 v[124:127], v[244:247], v[20:23], v[124:127]
	v_mfma_f32_16x16x32_bf16 v[136:139], v[236:239], v[4:7], v[0:3]
	v_mfma_f32_16x16x32_bf16 v[132:135], v[236:239], v[16:19], v[0:3]
	s_waitcnt lgkmcnt(4)
	v_mfma_f32_16x16x32_bf16 v[136:139], v[248:251], v[8:11], v[136:139]
	v_mfma_f32_16x16x32_bf16 v[132:135], v[248:251], v[20:23], v[132:135]
	s_waitcnt lgkmcnt(3)
	v_mfma_f32_16x16x32_bf16 v[148:151], v[220:223], v[24:27], v[82:85]
	s_waitcnt lgkmcnt(2)
	v_mfma_f32_16x16x32_bf16 v[120:123], v[224:227], v[12:15], v[120:123]
	v_mfma_f32_16x16x32_bf16 v[84:87], v[224:227], v[24:27], v[116:119]
	s_waitcnt lgkmcnt(1)
	v_mfma_f32_16x16x32_bf16 v[152:155], v[228:231], v[12:15], v[128:131]
	v_mfma_f32_16x16x32_bf16 v[156:159], v[228:231], v[24:27], v[124:127]
	v_mfma_f32_16x16x32_bf16 v[112:115], v[220:223], v[12:15], v[112:115]
	s_waitcnt lgkmcnt(0)
	v_mfma_f32_16x16x32_bf16 v[160:163], v[240:243], v[12:15], v[136:139]
	v_mfma_f32_16x16x32_bf16 v[164:167], v[240:243], v[24:27], v[132:135]
	s_nop 2
	s_setprio 0
	s_nop 3
	v_max3_f32 v80, v112, v113, v114
	v_max3_f32 v80, v80, v115, v120
	v_max3_f32 v80, v80, v121, v122
	v_max3_f32 v80, v80, v123, v152
	v_max3_f32 v80, v80, v153, v154
	v_max3_f32 v80, v80, v155, v160
	v_max3_f32 v80, v80, v161, v162
	v_max_f32_e32 v80, v80, v163
	v_mul_f32_e32 v80, 0x3e16c740, v80
	v_max_f32_e32 v80, s71, v80
	v_mov_b32_e32 v82, v80
	s_nop 1
	v_permlane16_swap_b32_e32 v80, v82
	v_max_f32_e32 v82, v82, v82
	v_max_f32_e32 v80, v80, v80
	v_max_f32_e32 v80, v80, v82
	v_mov_b32_e32 v82, v80
	s_nop 1
	v_permlane32_swap_b32_e32 v80, v82
	v_max3_f32 v144, v81, v80, v82
	v_sub_f32_e32 v80, v81, v144
	v_fma_f32 v81, v112, s70, -v144
	v_exp_f32_e32 v143, v81
	v_fma_f32 v81, v113, s70, -v144
	v_exp_f32_e32 v141, v81
	v_fma_f32 v81, v114, s70, -v144
	v_max3_f32 v112, v148, v149, v150
	v_max3_f32 v112, v112, v151, v84
	v_max3_f32 v112, v112, v85, v86
	v_max3_f32 v112, v112, v87, v156
	v_max3_f32 v112, v112, v157, v158
	v_max3_f32 v112, v112, v159, v164
	v_max3_f32 v112, v112, v165, v166
	v_max_f32_e32 v112, v112, v167
	v_mul_f32_e32 v112, 0x3e16c740, v112
	v_max_f32_e32 v112, s71, v112
	v_mov_b32_e32 v114, v112
	s_nop 1
	v_permlane16_swap_b32_e32 v112, v114
	v_max_f32_e32 v114, v114, v114
	v_max_f32_e32 v112, v112, v112
	v_max_f32_e32 v112, v112, v114
	v_mov_b32_e32 v114, v112
	v_exp_f32_e32 v139, v81
	v_fma_f32 v81, v115, s70, -v144
	v_permlane32_swap_b32_e32 v112, v114
	v_exp_f32_e32 v137, v81
	v_fma_f32 v81, v120, s70, -v144
	v_max3_f32 v146, v190, v112, v114
	v_exp_f32_e32 v135, v81
	v_fma_f32 v81, v121, s70, -v144
	v_fma_f32 v84, v84, s70, -v146
	v_exp_f32_e32 v133, v81
	v_fma_f32 v81, v122, s70, -v144
	v_exp_f32_e32 v134, v84
	v_fma_f32 v84, v85, s70, -v146
	v_exp_f32_e32 v131, v81
	v_fma_f32 v81, v123, s70, -v144
	v_exp_f32_e32 v132, v84
	v_fma_f32 v84, v86, s70, -v146
	v_exp_f32_e32 v129, v81
	v_fma_f32 v81, v152, s70, -v144
	v_exp_f32_e32 v130, v84
	v_fma_f32 v84, v87, s70, -v146
	v_exp_f32_e32 v127, v81
	v_fma_f32 v81, v153, s70, -v144
	v_exp_f32_e32 v128, v84
	v_fma_f32 v84, v156, s70, -v146
	v_exp_f32_e32 v125, v81
	v_fma_f32 v81, v154, s70, -v144
	v_exp_f32_e32 v126, v84
	v_fma_f32 v84, v157, s70, -v146
	v_exp_f32_e32 v123, v81
	v_fma_f32 v81, v155, s70, -v144
	v_fma_f32 v112, v148, s70, -v146
	v_exp_f32_e32 v124, v84
	v_fma_f32 v84, v158, s70, -v146
	v_exp_f32_e32 v119, v81
	v_fma_f32 v81, v160, s70, -v144
	v_exp_f32_e32 v142, v112
	v_fma_f32 v112, v149, s70, -v146
	v_exp_f32_e32 v122, v84
	v_fma_f32 v84, v159, s70, -v146
	v_exp_f32_e32 v115, v81
	v_fma_f32 v81, v161, s70, -v144
	v_exp_f32_e32 v140, v112
	v_fma_f32 v112, v150, s70, -v146
	v_exp_f32_e32 v118, v84
	v_fma_f32 v84, v164, s70, -v146
	v_fma_f32 v85, v166, s70, -v146
	v_exp_f32_e32 v113, v81
	v_fma_f32 v81, v162, s70, -v144
	v_exp_f32_e32 v110, v80
	v_fma_f32 v80, v163, s70, -v144
	v_sub_f32_e32 v116, v190, v146
	v_exp_f32_e32 v138, v112
	v_fma_f32 v112, v151, s70, -v146
	v_exp_f32_e32 v114, v84
	v_fma_f32 v84, v165, s70, -v146
	v_exp_f32_e32 v120, v85
	v_fma_f32 v85, v167, s70, -v146
	v_exp_f32_e32 v121, v81
	v_exp_f32_e32 v117, v80
	v_exp_f32_e32 v136, v112
	v_exp_f32_e32 v112, v84
	v_exp_f32_e32 v84, v116
	v_exp_f32_e32 v116, v85
	v_pk_mul_f32 v[70:71], v[70:71], v[110:111] op_sel_hi:[1,0]
	v_pk_mul_f32 v[68:69], v[68:69], v[110:111] op_sel_hi:[1,0]
	v_pk_mul_f32 v[66:67], v[66:67], v[110:111] op_sel_hi:[1,0]
	v_pk_mul_f32 v[64:65], v[64:65], v[110:111] op_sel_hi:[1,0]
	v_pk_mul_f32 v[74:75], v[74:75], v[110:111] op_sel_hi:[1,0]
	v_pk_mul_f32 v[72:73], v[72:73], v[110:111] op_sel_hi:[1,0]
	v_pk_mul_f32 v[82:83], v[78:79], v[110:111] op_sel_hi:[1,0]
	v_pk_mul_f32 v[80:81], v[76:77], v[110:111] op_sel_hi:[1,0]
	v_cvt_pk_bf16_f32 v152, v143, v141
	v_cvt_pk_bf16_f32 v153, v139, v137
	v_cvt_pk_bf16_f32 v154, v135, v133
	v_cvt_pk_bf16_f32 v155, v131, v129
	v_cvt_pk_bf16_f32 v76, v127, v125
	v_cvt_pk_bf16_f32 v77, v123, v119
	v_cvt_pk_bf16_f32 v78, v115, v113
	v_cvt_pk_bf16_f32 v79, v121, v117
	v_pk_mul_f32 v[54:55], v[54:55], v[84:85] op_sel_hi:[1,0]
	v_pk_mul_f32 v[52:53], v[52:53], v[84:85] op_sel_hi:[1,0]
	v_pk_mul_f32 v[50:51], v[50:51], v[84:85] op_sel_hi:[1,0]
	v_pk_mul_f32 v[48:49], v[48:49], v[84:85] op_sel_hi:[1,0]
	v_pk_mul_f32 v[58:59], v[58:59], v[84:85] op_sel_hi:[1,0]
	v_pk_mul_f32 v[56:57], v[56:57], v[84:85] op_sel_hi:[1,0]
	v_pk_mul_f32 v[62:63], v[62:63], v[84:85] op_sel_hi:[1,0]
	v_pk_mul_f32 v[60:61], v[60:61], v[84:85] op_sel_hi:[1,0]
	v_cvt_pk_bf16_f32 v148, v142, v140
	v_cvt_pk_bf16_f32 v149, v138, v136
	v_cvt_pk_bf16_f32 v150, v134, v132
	v_cvt_pk_bf16_f32 v151, v130, v128
	v_cvt_pk_bf16_f32 v156, v126, v124
	v_cvt_pk_bf16_f32 v157, v122, v118
	v_cvt_pk_bf16_f32 v158, v114, v112
	v_cvt_pk_bf16_f32 v159, v120, v116
	s_setprio 1
	v_add3_u32 v85, s11, v188, v189
	ds_read_b64_tr_b16 v[222:223], v85 offset:29184
	ds_read_b64_tr_b16 v[220:221], v85 offset:26624
	ds_read_b64_tr_b16 v[224:225], v85 offset:26656
	ds_read_b64_tr_b16 v[226:227], v85 offset:29216
	ds_read_b64_tr_b16 v[228:229], v85 offset:31744
	ds_read_b64_tr_b16 v[230:231], v85 offset:34304
	ds_read_b64_tr_b16 v[232:233], v85 offset:31776
	ds_read_b64_tr_b16 v[234:235], v85 offset:34336
	ds_read_b64_tr_b16 v[236:237], v85 offset:26688
	ds_read_b64_tr_b16 v[238:239], v85 offset:29248
	ds_read_b64_tr_b16 v[240:241], v85 offset:31808
	ds_read_b64_tr_b16 v[242:243], v85 offset:34368
	ds_read_b64_tr_b16 v[244:245], v85 offset:26720
	ds_read_b64_tr_b16 v[246:247], v85 offset:29280
	ds_read_b64_tr_b16 v[248:249], v85 offset:31840
	ds_read_b64_tr_b16 v[250:251], v85 offset:34400
	s_waitcnt lgkmcnt(14)
	v_mfma_f32_16x16x32_bf16 v[68:71], v[220:223], v[152:155], v[68:71]
	v_mfma_f32_16x16x32_bf16 v[52:55], v[220:223], v[148:151], v[52:55]
	s_waitcnt lgkmcnt(10)
	v_mfma_f32_16x16x32_bf16 v[68:71], v[228:231], v[76:79], v[68:71]
	v_mfma_f32_16x16x32_bf16 v[52:55], v[228:231], v[156:159], v[52:55]
	v_mfma_f32_16x16x32_bf16 v[64:67], v[224:227], v[152:155], v[64:67]
	v_mfma_f32_16x16x32_bf16 v[48:51], v[224:227], v[148:151], v[48:51]
	s_waitcnt lgkmcnt(8)
	v_mfma_f32_16x16x32_bf16 v[64:67], v[232:235], v[76:79], v[64:67]
	v_mfma_f32_16x16x32_bf16 v[48:51], v[232:235], v[156:159], v[48:51]
	s_waitcnt lgkmcnt(6)
	v_mfma_f32_16x16x32_bf16 v[72:75], v[236:239], v[152:155], v[72:75]
	v_mfma_f32_16x16x32_bf16 v[56:59], v[236:239], v[148:151], v[56:59]
	s_waitcnt lgkmcnt(4)
	v_mfma_f32_16x16x32_bf16 v[72:75], v[240:243], v[76:79], v[72:75]
	v_mfma_f32_16x16x32_bf16 v[56:59], v[240:243], v[156:159], v[56:59]
	s_waitcnt lgkmcnt(2)
	v_mfma_f32_16x16x32_bf16 v[60:63], v[244:247], v[148:151], v[60:63]
	v_mfma_f32_16x16x32_bf16 v[80:83], v[244:247], v[152:155], v[80:83]
	s_waitcnt lgkmcnt(0)
	v_mfma_f32_16x16x32_bf16 v[76:79], v[248:251], v[76:79], v[80:83]
	v_mfma_f32_16x16x32_bf16 v[60:63], v[248:251], v[156:159], v[60:63]
	s_nop 3
	s_setprio 0
	s_setprio 1
	ds_read_b128 v[220:223], v109 offset:13312
	ds_read_b128 v[224:227], v109 offset:13376
	ds_read_b128 v[228:231], v109 offset:16640
	ds_read_b128 v[232:235], v109 offset:19968
	ds_read_b128 v[236:239], v109 offset:23296
	ds_read_b128 v[240:243], v109 offset:16704
	ds_read_b128 v[244:247], v109 offset:20032
	ds_read_b128 v[248:251], v109 offset:23360
	s_waitcnt lgkmcnt(7)
	v_mfma_f32_16x16x32_bf16 v[148:151], v[220:223], v[4:7], v[0:3]
	v_mfma_f32_16x16x32_bf16 v[80:83], v[220:223], v[16:19], v[0:3]
	ds_read_b128 v[220:223], v109 offset:13440
	s_waitcnt lgkmcnt(7)
	v_mfma_f32_16x16x32_bf16 v[148:151], v[224:227], v[8:11], v[148:151]
	v_mfma_f32_16x16x32_bf16 v[80:83], v[224:227], v[20:23], v[80:83]
	ds_read_b128 v[224:227], v109 offset:16768
	s_waitcnt lgkmcnt(7)
	v_mfma_f32_16x16x32_bf16 v[156:159], v[228:231], v[4:7], v[0:3]
	v_mfma_f32_16x16x32_bf16 v[152:155], v[228:231], v[16:19], v[0:3]
	ds_read_b128 v[228:231], v109 offset:20096
	s_waitcnt lgkmcnt(5)
	v_mfma_f32_16x16x32_bf16 v[156:159], v[240:243], v[8:11], v[156:159]
	v_mfma_f32_16x16x32_bf16 v[152:155], v[240:243], v[20:23], v[152:155]
	ds_read_b128 v[240:243], v109 offset:23424
	v_mfma_f32_16x16x32_bf16 v[164:167], v[232:235], v[4:7], v[0:3]
	v_mfma_f32_16x16x32_bf16 v[160:163], v[232:235], v[16:19], v[0:3]
	s_waitcnt lgkmcnt(5)
	v_mfma_f32_16x16x32_bf16 v[164:167], v[244:247], v[8:11], v[164:167]
	v_mfma_f32_16x16x32_bf16 v[160:163], v[244:247], v[20:23], v[160:163]
	v_mfma_f32_16x16x32_bf16 v[190:193], v[236:239], v[4:7], v[0:3]
	v_mfma_f32_16x16x32_bf16 v[168:171], v[236:239], v[16:19], v[0:3]
	s_waitcnt lgkmcnt(4)
	v_mfma_f32_16x16x32_bf16 v[190:193], v[248:251], v[8:11], v[190:193]
	v_mfma_f32_16x16x32_bf16 v[168:171], v[248:251], v[20:23], v[168:171]
	s_waitcnt lgkmcnt(3)
	v_mfma_f32_16x16x32_bf16 v[148:151], v[220:223], v[12:15], v[148:151]
	v_mfma_f32_16x16x32_bf16 v[194:197], v[220:223], v[24:27], v[80:83]
	s_waitcnt lgkmcnt(2)
	v_mfma_f32_16x16x32_bf16 v[198:201], v[224:227], v[12:15], v[156:159]
	v_mfma_f32_16x16x32_bf16 v[202:205], v[224:227], v[24:27], v[152:155]
	s_waitcnt lgkmcnt(1)
	v_mfma_f32_16x16x32_bf16 v[206:209], v[228:231], v[12:15], v[164:167]
	v_mfma_f32_16x16x32_bf16 v[210:213], v[228:231], v[24:27], v[160:163]
	s_waitcnt lgkmcnt(0)
	v_mfma_f32_16x16x32_bf16 v[190:193], v[240:243], v[12:15], v[190:193]
	v_mfma_f32_16x16x32_bf16 v[214:217], v[240:243], v[24:27], v[168:171]
	s_nop 1
	s_setprio 0
	v_max3_f32 v80, v148, v149, v150
	v_max3_f32 v80, v80, v151, v198
	v_max3_f32 v80, v80, v199, v200
	v_max3_f32 v80, v80, v201, v206
	v_max3_f32 v80, v80, v207, v208
	v_max3_f32 v80, v80, v209, v190
	v_max3_f32 v80, v80, v191, v192
	v_max_f32_e32 v80, v80, v193
	v_mul_f32_e32 v80, 0x3e16c740, v80
	v_max_f32_e32 v80, s71, v80
	v_mov_b32_e32 v81, v80
	s_nop 1
	v_permlane16_swap_b32_e32 v80, v81
	v_max_f32_e32 v81, v81, v81
	v_max_f32_e32 v80, v80, v80
	v_max_f32_e32 v80, v80, v81
	v_mov_b32_e32 v81, v80
	s_nop 1
	v_permlane32_swap_b32_e32 v80, v81
	v_max3_f32 v81, v144, v80, v81
	v_fma_f32 v82, v148, s70, -v81
	v_exp_f32_e32 v171, v82
	v_fma_f32 v82, v149, s70, -v81
	v_exp_f32_e32 v169, v82
	v_fma_f32 v82, v150, s70, -v81
	v_exp_f32_e32 v167, v82
	v_fma_f32 v82, v151, s70, -v81
	v_exp_f32_e32 v165, v82
	v_fma_f32 v82, v198, s70, -v81
	v_exp_f32_e32 v163, v82
	v_fma_f32 v82, v199, s70, -v81
	v_exp_f32_e32 v161, v82
	v_fma_f32 v82, v200, s70, -v81
	v_exp_f32_e32 v159, v82
	v_fma_f32 v82, v201, s70, -v81
	v_exp_f32_e32 v157, v82
	v_fma_f32 v82, v206, s70, -v81
	v_exp_f32_e32 v155, v82
	v_fma_f32 v82, v207, s70, -v81
	v_exp_f32_e32 v153, v82
	v_fma_f32 v82, v208, s70, -v81
	v_exp_f32_e32 v151, v82
	v_fma_f32 v82, v209, s70, -v81
	v_exp_f32_e32 v147, v82
	v_fma_f32 v82, v190, s70, -v81
	v_exp_f32_e32 v87, v82
	v_fma_f32 v82, v191, s70, -v81
	v_exp_f32_e32 v83, v82
	v_fma_f32 v82, v192, s70, -v81
	v_exp_f32_e32 v149, v82
	v_fma_f32 v82, v193, s70, -v81
	v_exp_f32_e32 v145, v82
	v_max3_f32 v82, v194, v195, v196
	v_max3_f32 v82, v82, v197, v202
	v_max3_f32 v82, v82, v203, v204
	v_max3_f32 v82, v82, v205, v210
	v_max3_f32 v82, v82, v211, v212
	v_max3_f32 v82, v82, v213, v214
	v_max3_f32 v82, v82, v215, v216
	v_max_f32_e32 v82, v82, v217
	v_mul_f32_e32 v82, 0x3e16c740, v82
	v_max_f32_e32 v82, s71, v82
	v_mov_b32_e32 v86, v82
	s_nop 1
	v_permlane16_swap_b32_e32 v82, v86
	v_max_f32_e32 v86, v86, v86
	v_max_f32_e32 v82, v82, v82
	v_max_f32_e32 v82, v82, v86
	v_mov_b32_e32 v86, v82
	s_nop 1
	v_permlane32_swap_b32_e32 v82, v86
	v_max3_f32 v190, v146, v82, v86
	v_fma_f32 v82, v194, s70, -v190
	v_exp_f32_e32 v170, v82
	v_fma_f32 v82, v195, s70, -v190
	v_exp_f32_e32 v168, v82
	v_fma_f32 v82, v196, s70, -v190
	v_exp_f32_e32 v166, v82
	v_fma_f32 v82, v197, s70, -v190
	v_exp_f32_e32 v164, v82
	v_fma_f32 v82, v202, s70, -v190
	v_exp_f32_e32 v162, v82
	v_fma_f32 v82, v203, s70, -v190
	v_exp_f32_e32 v160, v82
	v_fma_f32 v82, v204, s70, -v190
	v_exp_f32_e32 v158, v82
	v_fma_f32 v82, v205, s70, -v190
	v_exp_f32_e32 v156, v82
	v_fma_f32 v82, v210, s70, -v190
	v_exp_f32_e32 v154, v82
	v_fma_f32 v82, v211, s70, -v190
	v_exp_f32_e32 v152, v82
	v_fma_f32 v82, v212, s70, -v190
	v_exp_f32_e32 v150, v82
	v_fma_f32 v82, v213, s70, -v190
	v_sub_f32_e32 v80, v144, v81
	v_sub_f32_e32 v109, v146, v190
	v_exp_f32_e32 v146, v82
	v_fma_f32 v82, v214, s70, -v190
	v_exp_f32_e32 v80, v80
	v_exp_f32_e32 v86, v82
	v_fma_f32 v82, v215, s70, -v190
	v_fma_f32 v144, v216, s70, -v190
	v_exp_f32_e32 v172, v109
	v_fma_f32 v109, v217, s70, -v190
	v_exp_f32_e32 v82, v82
	v_exp_f32_e32 v148, v144
	v_exp_f32_e32 v144, v109
	v_pk_mul_f32 v[70:71], v[70:71], v[80:81] op_sel_hi:[1,0]
	v_pk_mul_f32 v[68:69], v[68:69], v[80:81] op_sel_hi:[1,0]
	v_pk_mul_f32 v[66:67], v[66:67], v[80:81] op_sel_hi:[1,0]
	v_pk_mul_f32 v[64:65], v[64:65], v[80:81] op_sel_hi:[1,0]
	v_pk_mul_f32 v[74:75], v[74:75], v[80:81] op_sel_hi:[1,0]
	v_pk_mul_f32 v[72:73], v[72:73], v[80:81] op_sel_hi:[1,0]
	v_pk_mul_f32 v[200:201], v[78:79], v[80:81] op_sel_hi:[1,0]
	v_pk_mul_f32 v[198:199], v[76:77], v[80:81] op_sel_hi:[1,0]
	v_cvt_pk_bf16_f32 v76, v155, v153
	v_cvt_pk_bf16_f32 v77, v151, v147
	v_cvt_pk_bf16_f32 v78, v87, v83
	v_cvt_pk_bf16_f32 v79, v149, v145
	v_pk_mul_f32 v[54:55], v[54:55], v[172:173] op_sel_hi:[1,0]
	v_pk_mul_f32 v[52:53], v[52:53], v[172:173] op_sel_hi:[1,0]
	v_pk_mul_f32 v[50:51], v[50:51], v[172:173] op_sel_hi:[1,0]
	v_pk_mul_f32 v[48:49], v[48:49], v[172:173] op_sel_hi:[1,0]
	v_pk_mul_f32 v[58:59], v[58:59], v[172:173] op_sel_hi:[1,0]
	v_pk_mul_f32 v[56:57], v[56:57], v[172:173] op_sel_hi:[1,0]
	v_pk_mul_f32 v[62:63], v[62:63], v[172:173] op_sel_hi:[1,0]
	v_pk_mul_f32 v[60:61], v[60:61], v[172:173] op_sel_hi:[1,0]
	v_cvt_pk_bf16_f32 v206, v171, v169
	v_cvt_pk_bf16_f32 v207, v167, v165
	v_cvt_pk_bf16_f32 v208, v163, v161
	v_cvt_pk_bf16_f32 v209, v159, v157
	v_cvt_pk_bf16_f32 v192, v170, v168
	v_cvt_pk_bf16_f32 v193, v166, v164
	v_cvt_pk_bf16_f32 v194, v162, v160
	v_cvt_pk_bf16_f32 v195, v158, v156
	v_cvt_pk_bf16_f32 v202, v154, v152
	v_cvt_pk_bf16_f32 v203, v150, v146
	v_cvt_pk_bf16_f32 v204, v86, v82
	v_cvt_pk_bf16_f32 v205, v148, v144
	s_setprio 1
	ds_read_b64_tr_b16 v[222:223], v85 offset:39424
	ds_read_b64_tr_b16 v[220:221], v85 offset:36864
	ds_read_b64_tr_b16 v[224:225], v85 offset:36896
	ds_read_b64_tr_b16 v[226:227], v85 offset:39456
	ds_read_b64_tr_b16 v[228:229], v85 offset:41984
	ds_read_b64_tr_b16 v[230:231], v85 offset:44544
	ds_read_b64_tr_b16 v[232:233], v85 offset:42016
	ds_read_b64_tr_b16 v[234:235], v85 offset:44576
	ds_read_b64_tr_b16 v[236:237], v85 offset:36928
	ds_read_b64_tr_b16 v[238:239], v85 offset:39488
	ds_read_b64_tr_b16 v[240:241], v85 offset:42048
	ds_read_b64_tr_b16 v[242:243], v85 offset:44608
	ds_read_b64_tr_b16 v[244:245], v85 offset:36960
	ds_read_b64_tr_b16 v[246:247], v85 offset:39520
	ds_read_b64_tr_b16 v[248:249], v85 offset:42080
	ds_read_b64_tr_b16 v[250:251], v85 offset:44640
	s_waitcnt lgkmcnt(14)
	v_mfma_f32_16x16x32_bf16 v[68:71], v[220:223], v[206:209], v[68:71]
	v_mfma_f32_16x16x32_bf16 v[52:55], v[220:223], v[192:195], v[52:55]
	s_waitcnt lgkmcnt(10)
	v_mfma_f32_16x16x32_bf16 v[68:71], v[228:231], v[76:79], v[68:71]
	v_mfma_f32_16x16x32_bf16 v[52:55], v[228:231], v[202:205], v[52:55]
	v_mfma_f32_16x16x32_bf16 v[64:67], v[224:227], v[206:209], v[64:67]
	v_mfma_f32_16x16x32_bf16 v[48:51], v[224:227], v[192:195], v[48:51]
	s_waitcnt lgkmcnt(8)
	v_mfma_f32_16x16x32_bf16 v[64:67], v[232:235], v[76:79], v[64:67]
	v_mfma_f32_16x16x32_bf16 v[48:51], v[232:235], v[202:205], v[48:51]
	s_waitcnt lgkmcnt(6)
	v_mfma_f32_16x16x32_bf16 v[72:75], v[236:239], v[206:209], v[72:75]
	v_mfma_f32_16x16x32_bf16 v[56:59], v[236:239], v[192:195], v[56:59]
	s_waitcnt lgkmcnt(4)
	v_mfma_f32_16x16x32_bf16 v[72:75], v[240:243], v[76:79], v[72:75]
	v_mfma_f32_16x16x32_bf16 v[56:59], v[240:243], v[202:205], v[56:59]
	s_waitcnt lgkmcnt(2)
	v_mfma_f32_16x16x32_bf16 v[60:63], v[244:247], v[192:195], v[60:63]
	v_mfma_f32_16x16x32_bf16 v[196:199], v[244:247], v[206:209], v[198:201]
	s_waitcnt lgkmcnt(0)
	v_mfma_f32_16x16x32_bf16 v[76:79], v[248:251], v[76:79], v[196:199]
	v_mfma_f32_16x16x32_bf16 v[60:63], v[248:251], v[202:205], v[60:63]
	s_nop 3
	s_setprio 0
	s_add_i32 s22, s10, 1
	s_cmp_ge_u32 s22, s19
	s_cbranch_scc1 .LBB0_1213
	s_bitcmp1_b32 s22, 0
	s_cselect_b32 s11, 0xb800, 0
	v_add3_u32 v85, s11, v95, v96
	s_waitcnt vmcnt(0)
	ds_write_b128 v85, v[28:31]
	v_add3_u32 v85, s11, v99, v96
	ds_write_b128 v85, v[36:39]
	v_add3_u32 v85, s11, v185, v96
	ds_write_b128 v85, v[32:35] offset:26624
	v_add3_u32 v85, s11, v186, v96
	ds_write_b128 v85, v[40:43] offset:26624
	v_add3_u32 v85, s11, v111, v98
	ds_write_b128 v85, v[44:47] offset:128

.LBB0_1709:
	flat_load_dword v4, v[0:1] sc1
	s_waitcnt vmcnt(0) lgkmcnt(0)
	v_readfirstlane_b32 s14, v4
	s_cmp_lt_u32 s14, 64
	s_cselect_b64 s[18:19], -1, 0
	s_and_b64 vcc, exec, s[18:19]
	s_cbranch_vccnz .LBB0_1711
.LBB0_1711:
	s_mov_b64 s[14:15], -1
	s_andn2_b64 vcc, exec, s[18:19]
	s_mov_b64 s[18:19], -1
	s_cbranch_vccnz .LBB0_1708
	s_and_b32 s14, s20, 0xff
	s_cmp_lg_u32 s14, 0
	s_cselect_b64 s[18:19], -1, 0
	s_cmp_eq_u32 s14, 0
	s_cbranch_scc1 .LBB0_1714
	s_mov_b64 s[14:15], -1
	s_andn2_b64 vcc, exec, s[18:19]
	s_mov_b64 s[18:19], -1
	s_cbranch_vccnz .LBB0_1708
	s_branch .LBB0_1715

.LBB0_1738:
	v_mov_b64_e32 v[144:145], s[50:51]
	s_waitcnt vmcnt(0)
	flat_load_dword v144, v[144:145] sc1
	s_waitcnt vmcnt(0) lgkmcnt(0)
	v_readfirstlane_b32 s68, v144
	s_cmp_lt_u32 s68, 64
	s_cselect_b64 s[70:71], -1, 0
	s_and_b64 vcc, exec, s[70:71]
	s_cbranch_vccnz .LBB0_1740
.LBB0_1740:
	s_mov_b64 s[68:69], -1
	s_andn2_b64 vcc, exec, s[70:71]
	s_mov_b64 s[70:71], -1
	s_cbranch_vccnz .LBB0_1737
	s_and_b32 s68, s20, 0xff
	s_cmp_lg_u32 s68, 0
	s_cselect_b64 s[70:71], -1, 0
	s_cmp_eq_u32 s68, 0
	s_cbranch_scc1 .LBB0_1743
	s_mov_b64 s[68:69], -1
	s_andn2_b64 vcc, exec, s[70:71]
	s_mov_b64 s[70:71], -1
	s_cbranch_vccnz .LBB0_1737
	s_branch .LBB0_1744

.LBB0_2968:
	s_bitcmp1_b32 s10, 0
	s_cselect_b32 s11, 0xb800, 0
	s_setprio 1
	v_or_b32_e32 v80, s11, v94
	v_add_u32_e32 v109, v80, v186
	ds_read_b128 v[220:223], v109
	ds_read_b128 v[224:227], v109 offset:64
	ds_read_b128 v[228:231], v109 offset:3328
	ds_read_b128 v[232:235], v109 offset:6656
	ds_read_b128 v[236:239], v109 offset:9984
	ds_read_b128 v[240:243], v109 offset:3392
	ds_read_b128 v[244:247], v109 offset:6720
	ds_read_b128 v[248:251], v109 offset:10048
	s_waitcnt lgkmcnt(7)
	v_mfma_f32_16x16x32_bf16 v[112:115], v[220:223], v[4:7], v[0:3]
	v_mfma_f32_16x16x32_bf16 v[82:85], v[220:223], v[16:19], v[0:3]
	ds_read_b128 v[220:223], v109 offset:128
	s_waitcnt lgkmcnt(7)
	v_mfma_f32_16x16x32_bf16 v[112:115], v[224:227], v[8:11], v[112:115]
	v_mfma_f32_16x16x32_bf16 v[82:85], v[224:227], v[20:23], v[82:85]
	ds_read_b128 v[224:227], v109 offset:3456
	s_waitcnt lgkmcnt(7)
	v_mfma_f32_16x16x32_bf16 v[120:123], v[228:231], v[4:7], v[0:3]
	v_mfma_f32_16x16x32_bf16 v[116:119], v[228:231], v[16:19], v[0:3]
	ds_read_b128 v[228:231], v109 offset:6784
	s_waitcnt lgkmcnt(5)
	v_mfma_f32_16x16x32_bf16 v[120:123], v[240:243], v[8:11], v[120:123]
	v_mfma_f32_16x16x32_bf16 v[116:119], v[240:243], v[20:23], v[116:119]
	ds_read_b128 v[240:243], v109 offset:10112
	v_mfma_f32_16x16x32_bf16 v[128:131], v[232:235], v[4:7], v[0:3]
	v_mfma_f32_16x16x32_bf16 v[124:127], v[232:235], v[16:19], v[0:3]
	s_waitcnt lgkmcnt(5)
	v_mfma_f32_16x16x32_bf16 v[128:131], v[244:247], v[8:11], v[128:131]
	v_mfma_f32_16x16x32_bf16 v[124:127], v[244:247], v[20:23], v[124:127]
	v_mfma_f32_16x16x32_bf16 v[136:139], v[236:239], v[4:7], v[0:3]
	v_mfma_f32_16x16x32_bf16 v[132:135], v[236:239], v[16:19], v[0:3]
	s_waitcnt lgkmcnt(4)
	v_mfma_f32_16x16x32_bf16 v[136:139], v[248:251], v[8:11], v[136:139]
	v_mfma_f32_16x16x32_bf16 v[132:135], v[248:251], v[20:23], v[132:135]
	s_waitcnt lgkmcnt(3)
	v_mfma_f32_16x16x32_bf16 v[148:151], v[220:223], v[24:27], v[82:85]
	s_waitcnt lgkmcnt(2)
	v_mfma_f32_16x16x32_bf16 v[120:123], v[224:227], v[12:15], v[120:123]
	v_mfma_f32_16x16x32_bf16 v[84:87], v[224:227], v[24:27], v[116:119]
	s_waitcnt lgkmcnt(1)
	v_mfma_f32_16x16x32_bf16 v[152:155], v[228:231], v[12:15], v[128:131]
	v_mfma_f32_16x16x32_bf16 v[156:159], v[228:231], v[24:27], v[124:127]
	v_mfma_f32_16x16x32_bf16 v[112:115], v[220:223], v[12:15], v[112:115]
	s_waitcnt lgkmcnt(0)
	v_mfma_f32_16x16x32_bf16 v[160:163], v[240:243], v[12:15], v[136:139]
	v_mfma_f32_16x16x32_bf16 v[164:167], v[240:243], v[24:27], v[132:135]
	s_nop 2
	s_setprio 0
	s_nop 3
	v_max3_f32 v80, v112, v113, v114
	v_max3_f32 v80, v80, v115, v120
	v_max3_f32 v80, v80, v121, v122
	v_max3_f32 v80, v80, v123, v152
	v_max3_f32 v80, v80, v153, v154
	v_max3_f32 v80, v80, v155, v160
	v_max3_f32 v80, v80, v161, v162
	v_max_f32_e32 v80, v80, v163
	v_mul_f32_e32 v80, 0x3e16c740, v80
	v_max_f32_e32 v80, s68, v80
	v_mov_b32_e32 v82, v80
	s_nop 1
	v_permlane16_swap_b32_e32 v80, v82
	v_max_f32_e32 v82, v82, v82
	v_max_f32_e32 v80, v80, v80
	v_max_f32_e32 v80, v80, v82
	v_mov_b32_e32 v82, v80
	s_nop 1
	v_permlane32_swap_b32_e32 v80, v82
	v_max3_f32 v144, v81, v80, v82
	v_sub_f32_e32 v80, v81, v144
	v_fma_f32 v81, v112, s38, -v144
	v_exp_f32_e32 v143, v81
	v_fma_f32 v81, v113, s38, -v144
	v_exp_f32_e32 v141, v81
	v_fma_f32 v81, v114, s38, -v144
	v_max3_f32 v112, v148, v149, v150
	v_max3_f32 v112, v112, v151, v84
	v_max3_f32 v112, v112, v85, v86
	v_max3_f32 v112, v112, v87, v156
	v_max3_f32 v112, v112, v157, v158
	v_max3_f32 v112, v112, v159, v164
	v_max3_f32 v112, v112, v165, v166
	v_max_f32_e32 v112, v112, v167
	v_mul_f32_e32 v112, 0x3e16c740, v112
	v_max_f32_e32 v112, s68, v112
	v_mov_b32_e32 v114, v112
	s_nop 1
	v_permlane16_swap_b32_e32 v112, v114
	v_max_f32_e32 v114, v114, v114
	v_max_f32_e32 v112, v112, v112
	v_max_f32_e32 v112, v112, v114
	v_mov_b32_e32 v114, v112
	v_exp_f32_e32 v139, v81
	v_fma_f32 v81, v115, s38, -v144
	v_permlane32_swap_b32_e32 v112, v114
	v_exp_f32_e32 v137, v81
	v_fma_f32 v81, v120, s38, -v144
	v_max3_f32 v146, v189, v112, v114
	v_exp_f32_e32 v135, v81
	v_fma_f32 v81, v121, s38, -v144
	v_fma_f32 v84, v84, s38, -v146
	v_exp_f32_e32 v133, v81
	v_fma_f32 v81, v122, s38, -v144
	v_exp_f32_e32 v134, v84
	v_fma_f32 v84, v85, s38, -v146
	v_exp_f32_e32 v131, v81
	v_fma_f32 v81, v123, s38, -v144
	v_exp_f32_e32 v132, v84
	v_fma_f32 v84, v86, s38, -v146
	v_exp_f32_e32 v129, v81
	v_fma_f32 v81, v152, s38, -v144
	v_exp_f32_e32 v130, v84
	v_fma_f32 v84, v87, s38, -v146
	v_exp_f32_e32 v127, v81
	v_fma_f32 v81, v153, s38, -v144
	v_exp_f32_e32 v128, v84
	v_fma_f32 v84, v156, s38, -v146
	v_exp_f32_e32 v125, v81
	v_fma_f32 v81, v154, s38, -v144
	v_exp_f32_e32 v126, v84
	v_fma_f32 v84, v157, s38, -v146
	v_exp_f32_e32 v123, v81
	v_fma_f32 v81, v155, s38, -v144
	v_fma_f32 v112, v148, s38, -v146
	v_exp_f32_e32 v124, v84
	v_fma_f32 v84, v158, s38, -v146
	v_exp_f32_e32 v119, v81
	v_fma_f32 v81, v160, s38, -v144
	v_exp_f32_e32 v142, v112
	v_fma_f32 v112, v149, s38, -v146
	v_exp_f32_e32 v122, v84
	v_fma_f32 v84, v159, s38, -v146
	v_exp_f32_e32 v115, v81
	v_fma_f32 v81, v161, s38, -v144
	v_exp_f32_e32 v140, v112
	v_fma_f32 v112, v150, s38, -v146
	v_exp_f32_e32 v118, v84
	v_fma_f32 v84, v164, s38, -v146
	v_fma_f32 v85, v166, s38, -v146
	v_exp_f32_e32 v113, v81
	v_fma_f32 v81, v162, s38, -v144
	v_exp_f32_e32 v110, v80
	v_fma_f32 v80, v163, s38, -v144
	v_sub_f32_e32 v116, v189, v146
	v_exp_f32_e32 v138, v112
	v_fma_f32 v112, v151, s38, -v146
	v_exp_f32_e32 v114, v84
	v_fma_f32 v84, v165, s38, -v146
	v_exp_f32_e32 v120, v85
	v_fma_f32 v85, v167, s38, -v146
	v_exp_f32_e32 v121, v81
	v_exp_f32_e32 v117, v80
	v_exp_f32_e32 v136, v112
	v_exp_f32_e32 v112, v84
	v_exp_f32_e32 v84, v116
	v_exp_f32_e32 v116, v85
	v_pk_mul_f32 v[70:71], v[70:71], v[110:111] op_sel_hi:[1,0]
	v_pk_mul_f32 v[68:69], v[68:69], v[110:111] op_sel_hi:[1,0]
	v_pk_mul_f32 v[66:67], v[66:67], v[110:111] op_sel_hi:[1,0]
	v_pk_mul_f32 v[64:65], v[64:65], v[110:111] op_sel_hi:[1,0]
	v_pk_mul_f32 v[74:75], v[74:75], v[110:111] op_sel_hi:[1,0]
	v_pk_mul_f32 v[72:73], v[72:73], v[110:111] op_sel_hi:[1,0]
	v_pk_mul_f32 v[82:83], v[78:79], v[110:111] op_sel_hi:[1,0]
	v_pk_mul_f32 v[80:81], v[76:77], v[110:111] op_sel_hi:[1,0]
	v_cvt_pk_bf16_f32 v152, v143, v141
	v_cvt_pk_bf16_f32 v153, v139, v137
	v_cvt_pk_bf16_f32 v154, v135, v133
	v_cvt_pk_bf16_f32 v155, v131, v129
	v_cvt_pk_bf16_f32 v76, v127, v125
	v_cvt_pk_bf16_f32 v77, v123, v119
	v_cvt_pk_bf16_f32 v78, v115, v113
	v_cvt_pk_bf16_f32 v79, v121, v117
	v_pk_mul_f32 v[54:55], v[54:55], v[84:85] op_sel_hi:[1,0]
	v_pk_mul_f32 v[52:53], v[52:53], v[84:85] op_sel_hi:[1,0]
	v_pk_mul_f32 v[50:51], v[50:51], v[84:85] op_sel_hi:[1,0]
	v_pk_mul_f32 v[48:49], v[48:49], v[84:85] op_sel_hi:[1,0]
	v_pk_mul_f32 v[58:59], v[58:59], v[84:85] op_sel_hi:[1,0]
	v_pk_mul_f32 v[56:57], v[56:57], v[84:85] op_sel_hi:[1,0]
	v_pk_mul_f32 v[62:63], v[62:63], v[84:85] op_sel_hi:[1,0]
	v_pk_mul_f32 v[60:61], v[60:61], v[84:85] op_sel_hi:[1,0]
	v_cvt_pk_bf16_f32 v148, v142, v140
	v_cvt_pk_bf16_f32 v149, v138, v136
	v_cvt_pk_bf16_f32 v150, v134, v132
	v_cvt_pk_bf16_f32 v151, v130, v128
	v_cvt_pk_bf16_f32 v156, v126, v124
	v_cvt_pk_bf16_f32 v157, v122, v118
	v_cvt_pk_bf16_f32 v158, v114, v112
	v_cvt_pk_bf16_f32 v159, v120, v116
	s_setprio 1
	v_add3_u32 v85, s11, v187, v188
	ds_read_b64_tr_b16 v[222:223], v85 offset:29184
	ds_read_b64_tr_b16 v[220:221], v85 offset:26624
	ds_read_b64_tr_b16 v[224:225], v85 offset:26656
	ds_read_b64_tr_b16 v[226:227], v85 offset:29216
	ds_read_b64_tr_b16 v[228:229], v85 offset:31744
	ds_read_b64_tr_b16 v[230:231], v85 offset:34304
	ds_read_b64_tr_b16 v[232:233], v85 offset:31776
	ds_read_b64_tr_b16 v[234:235], v85 offset:34336
	ds_read_b64_tr_b16 v[236:237], v85 offset:26688
	ds_read_b64_tr_b16 v[238:239], v85 offset:29248
	ds_read_b64_tr_b16 v[240:241], v85 offset:31808
	ds_read_b64_tr_b16 v[242:243], v85 offset:34368
	ds_read_b64_tr_b16 v[244:245], v85 offset:26720
	ds_read_b64_tr_b16 v[246:247], v85 offset:29280
	ds_read_b64_tr_b16 v[248:249], v85 offset:31840
	ds_read_b64_tr_b16 v[250:251], v85 offset:34400
	s_waitcnt lgkmcnt(14)
	v_mfma_f32_16x16x32_bf16 v[68:71], v[220:223], v[152:155], v[68:71]
	v_mfma_f32_16x16x32_bf16 v[52:55], v[220:223], v[148:151], v[52:55]
	s_waitcnt lgkmcnt(10)
	v_mfma_f32_16x16x32_bf16 v[68:71], v[228:231], v[76:79], v[68:71]
	v_mfma_f32_16x16x32_bf16 v[52:55], v[228:231], v[156:159], v[52:55]
	v_mfma_f32_16x16x32_bf16 v[64:67], v[224:227], v[152:155], v[64:67]
	v_mfma_f32_16x16x32_bf16 v[48:51], v[224:227], v[148:151], v[48:51]
	s_waitcnt lgkmcnt(8)
	v_mfma_f32_16x16x32_bf16 v[64:67], v[232:235], v[76:79], v[64:67]
	v_mfma_f32_16x16x32_bf16 v[48:51], v[232:235], v[156:159], v[48:51]
	s_waitcnt lgkmcnt(6)
	v_mfma_f32_16x16x32_bf16 v[72:75], v[236:239], v[152:155], v[72:75]
	v_mfma_f32_16x16x32_bf16 v[56:59], v[236:239], v[148:151], v[56:59]
	s_waitcnt lgkmcnt(4)
	v_mfma_f32_16x16x32_bf16 v[72:75], v[240:243], v[76:79], v[72:75]
	v_mfma_f32_16x16x32_bf16 v[56:59], v[240:243], v[156:159], v[56:59]
	s_waitcnt lgkmcnt(2)
	v_mfma_f32_16x16x32_bf16 v[60:63], v[244:247], v[148:151], v[60:63]
	v_mfma_f32_16x16x32_bf16 v[80:83], v[244:247], v[152:155], v[80:83]
	s_waitcnt lgkmcnt(0)
	v_mfma_f32_16x16x32_bf16 v[76:79], v[248:251], v[76:79], v[80:83]
	v_mfma_f32_16x16x32_bf16 v[60:63], v[248:251], v[156:159], v[60:63]
	s_nop 3
	s_setprio 0
	s_setprio 1
	ds_read_b128 v[220:223], v109 offset:13312
	ds_read_b128 v[224:227], v109 offset:13376
	ds_read_b128 v[228:231], v109 offset:16640
	ds_read_b128 v[232:235], v109 offset:19968
	ds_read_b128 v[236:239], v109 offset:23296
	ds_read_b128 v[240:243], v109 offset:16704
	ds_read_b128 v[244:247], v109 offset:20032
	ds_read_b128 v[248:251], v109 offset:23360
	s_waitcnt lgkmcnt(7)
	v_mfma_f32_16x16x32_bf16 v[148:151], v[220:223], v[4:7], v[0:3]
	v_mfma_f32_16x16x32_bf16 v[80:83], v[220:223], v[16:19], v[0:3]
	ds_read_b128 v[220:223], v109 offset:13440
	s_waitcnt lgkmcnt(7)
	v_mfma_f32_16x16x32_bf16 v[148:151], v[224:227], v[8:11], v[148:151]
	v_mfma_f32_16x16x32_bf16 v[80:83], v[224:227], v[20:23], v[80:83]
	ds_read_b128 v[224:227], v109 offset:16768
	s_waitcnt lgkmcnt(7)
	v_mfma_f32_16x16x32_bf16 v[156:159], v[228:231], v[4:7], v[0:3]
	v_mfma_f32_16x16x32_bf16 v[152:155], v[228:231], v[16:19], v[0:3]
	ds_read_b128 v[228:231], v109 offset:20096
	s_waitcnt lgkmcnt(5)
	v_mfma_f32_16x16x32_bf16 v[156:159], v[240:243], v[8:11], v[156:159]
	v_mfma_f32_16x16x32_bf16 v[152:155], v[240:243], v[20:23], v[152:155]
	ds_read_b128 v[240:243], v109 offset:23424
	v_mfma_f32_16x16x32_bf16 v[164:167], v[232:235], v[4:7], v[0:3]
	v_mfma_f32_16x16x32_bf16 v[160:163], v[232:235], v[16:19], v[0:3]
	s_waitcnt lgkmcnt(5)
	v_mfma_f32_16x16x32_bf16 v[164:167], v[244:247], v[8:11], v[164:167]
	v_mfma_f32_16x16x32_bf16 v[160:163], v[244:247], v[20:23], v[160:163]
	v_mfma_f32_16x16x32_bf16 v[190:193], v[236:239], v[4:7], v[0:3]
	v_mfma_f32_16x16x32_bf16 v[168:171], v[236:239], v[16:19], v[0:3]
	s_waitcnt lgkmcnt(4)
	v_mfma_f32_16x16x32_bf16 v[190:193], v[248:251], v[8:11], v[190:193]
	v_mfma_f32_16x16x32_bf16 v[168:171], v[248:251], v[20:23], v[168:171]
	s_waitcnt lgkmcnt(3)
	v_mfma_f32_16x16x32_bf16 v[148:151], v[220:223], v[12:15], v[148:151]
	v_mfma_f32_16x16x32_bf16 v[194:197], v[220:223], v[24:27], v[80:83]
	s_waitcnt lgkmcnt(2)
	v_mfma_f32_16x16x32_bf16 v[198:201], v[224:227], v[12:15], v[156:159]
	v_mfma_f32_16x16x32_bf16 v[202:205], v[224:227], v[24:27], v[152:155]
	s_waitcnt lgkmcnt(1)
	v_mfma_f32_16x16x32_bf16 v[206:209], v[228:231], v[12:15], v[164:167]
	v_mfma_f32_16x16x32_bf16 v[210:213], v[228:231], v[24:27], v[160:163]
	s_waitcnt lgkmcnt(0)
	v_mfma_f32_16x16x32_bf16 v[190:193], v[240:243], v[12:15], v[190:193]
	v_mfma_f32_16x16x32_bf16 v[214:217], v[240:243], v[24:27], v[168:171]
	s_nop 1
	s_setprio 0
	v_max3_f32 v80, v148, v149, v150
	v_max3_f32 v80, v80, v151, v198
	v_max3_f32 v80, v80, v199, v200
	v_max3_f32 v80, v80, v201, v206
	v_max3_f32 v80, v80, v207, v208
	v_max3_f32 v80, v80, v209, v190
	v_max3_f32 v80, v80, v191, v192
	v_max_f32_e32 v80, v80, v193
	v_mul_f32_e32 v80, 0x3e16c740, v80
	v_max_f32_e32 v80, s68, v80
	v_mov_b32_e32 v81, v80
	s_nop 1
	v_permlane16_swap_b32_e32 v80, v81
	v_max_f32_e32 v81, v81, v81
	v_max_f32_e32 v80, v80, v80
	v_max_f32_e32 v80, v80, v81
	v_mov_b32_e32 v81, v80
	s_nop 1
	v_permlane32_swap_b32_e32 v80, v81
	v_max3_f32 v81, v144, v80, v81
	v_fma_f32 v82, v148, s38, -v81
	v_exp_f32_e32 v171, v82
	v_fma_f32 v82, v149, s38, -v81
	v_exp_f32_e32 v169, v82
	v_fma_f32 v82, v150, s38, -v81
	v_exp_f32_e32 v167, v82
	v_fma_f32 v82, v151, s38, -v81
	v_exp_f32_e32 v165, v82
	v_fma_f32 v82, v198, s38, -v81
	v_exp_f32_e32 v163, v82
	v_fma_f32 v82, v199, s38, -v81
	v_exp_f32_e32 v161, v82
	v_fma_f32 v82, v200, s38, -v81
	v_exp_f32_e32 v159, v82
	v_fma_f32 v82, v201, s38, -v81
	v_exp_f32_e32 v157, v82
	v_fma_f32 v82, v206, s38, -v81
	v_exp_f32_e32 v155, v82
	v_fma_f32 v82, v207, s38, -v81
	v_exp_f32_e32 v153, v82
	v_fma_f32 v82, v208, s38, -v81
	v_exp_f32_e32 v151, v82
	v_fma_f32 v82, v209, s38, -v81
	v_exp_f32_e32 v147, v82
	v_fma_f32 v82, v190, s38, -v81
	v_exp_f32_e32 v87, v82
	v_fma_f32 v82, v191, s38, -v81
	v_exp_f32_e32 v83, v82
	v_fma_f32 v82, v192, s38, -v81
	v_exp_f32_e32 v149, v82
	v_fma_f32 v82, v193, s38, -v81
	v_exp_f32_e32 v145, v82
	v_max3_f32 v82, v194, v195, v196
	v_max3_f32 v82, v82, v197, v202
	v_max3_f32 v82, v82, v203, v204
	v_max3_f32 v82, v82, v205, v210
	v_max3_f32 v82, v82, v211, v212
	v_max3_f32 v82, v82, v213, v214
	v_max3_f32 v82, v82, v215, v216
	v_max_f32_e32 v82, v82, v217
	v_mul_f32_e32 v82, 0x3e16c740, v82
	v_max_f32_e32 v82, s68, v82
	v_mov_b32_e32 v86, v82
	s_nop 1
	v_permlane16_swap_b32_e32 v82, v86
	v_max_f32_e32 v86, v86, v86
	v_max_f32_e32 v82, v82, v82
	v_max_f32_e32 v82, v82, v86
	v_mov_b32_e32 v86, v82
	s_nop 1
	v_permlane32_swap_b32_e32 v82, v86
	v_max3_f32 v189, v146, v82, v86
	v_fma_f32 v82, v194, s38, -v189
	v_exp_f32_e32 v170, v82
	v_fma_f32 v82, v195, s38, -v189
	v_exp_f32_e32 v168, v82
	v_fma_f32 v82, v196, s38, -v189
	v_exp_f32_e32 v166, v82
	v_fma_f32 v82, v197, s38, -v189
	v_exp_f32_e32 v164, v82
	v_fma_f32 v82, v202, s38, -v189
	v_exp_f32_e32 v162, v82
	v_fma_f32 v82, v203, s38, -v189
	v_exp_f32_e32 v160, v82
	v_fma_f32 v82, v204, s38, -v189
	v_exp_f32_e32 v158, v82
	v_fma_f32 v82, v205, s38, -v189
	v_exp_f32_e32 v156, v82
	v_fma_f32 v82, v210, s38, -v189
	v_exp_f32_e32 v154, v82
	v_fma_f32 v82, v211, s38, -v189
	v_exp_f32_e32 v152, v82
	v_fma_f32 v82, v212, s38, -v189
	v_exp_f32_e32 v150, v82
	v_fma_f32 v82, v213, s38, -v189
	v_sub_f32_e32 v80, v144, v81
	v_sub_f32_e32 v109, v146, v189
	v_exp_f32_e32 v146, v82
	v_fma_f32 v82, v214, s38, -v189
	v_exp_f32_e32 v80, v80
	v_exp_f32_e32 v86, v82
	v_fma_f32 v82, v215, s38, -v189
	v_fma_f32 v144, v216, s38, -v189
	v_exp_f32_e32 v172, v109
	v_fma_f32 v109, v217, s38, -v189
	v_exp_f32_e32 v82, v82
	v_exp_f32_e32 v148, v144
	v_exp_f32_e32 v144, v109
	v_pk_mul_f32 v[70:71], v[70:71], v[80:81] op_sel_hi:[1,0]
	v_pk_mul_f32 v[68:69], v[68:69], v[80:81] op_sel_hi:[1,0]
	v_pk_mul_f32 v[66:67], v[66:67], v[80:81] op_sel_hi:[1,0]
	v_pk_mul_f32 v[64:65], v[64:65], v[80:81] op_sel_hi:[1,0]
	v_pk_mul_f32 v[74:75], v[74:75], v[80:81] op_sel_hi:[1,0]
	v_pk_mul_f32 v[72:73], v[72:73], v[80:81] op_sel_hi:[1,0]
	v_pk_mul_f32 v[192:193], v[78:79], v[80:81] op_sel_hi:[1,0]
	v_pk_mul_f32 v[190:191], v[76:77], v[80:81] op_sel_hi:[1,0]
	v_cvt_pk_bf16_f32 v76, v155, v153
	v_cvt_pk_bf16_f32 v77, v151, v147
	v_cvt_pk_bf16_f32 v78, v87, v83
	v_cvt_pk_bf16_f32 v79, v149, v145
	v_pk_mul_f32 v[54:55], v[54:55], v[172:173] op_sel_hi:[1,0]
	v_pk_mul_f32 v[52:53], v[52:53], v[172:173] op_sel_hi:[1,0]
	v_pk_mul_f32 v[50:51], v[50:51], v[172:173] op_sel_hi:[1,0]
	v_pk_mul_f32 v[48:49], v[48:49], v[172:173] op_sel_hi:[1,0]
	v_pk_mul_f32 v[58:59], v[58:59], v[172:173] op_sel_hi:[1,0]
	v_pk_mul_f32 v[56:57], v[56:57], v[172:173] op_sel_hi:[1,0]
	v_pk_mul_f32 v[62:63], v[62:63], v[172:173] op_sel_hi:[1,0]
	v_pk_mul_f32 v[60:61], v[60:61], v[172:173] op_sel_hi:[1,0]
	v_cvt_pk_bf16_f32 v198, v171, v169
	v_cvt_pk_bf16_f32 v199, v167, v165
	v_cvt_pk_bf16_f32 v200, v163, v161
	v_cvt_pk_bf16_f32 v201, v159, v157
	v_cvt_pk_bf16_f32 v194, v170, v168
	v_cvt_pk_bf16_f32 v195, v166, v164
	v_cvt_pk_bf16_f32 v196, v162, v160
	v_cvt_pk_bf16_f32 v197, v158, v156
	v_cvt_pk_bf16_f32 v202, v154, v152
	v_cvt_pk_bf16_f32 v203, v150, v146
	v_cvt_pk_bf16_f32 v204, v86, v82
	v_cvt_pk_bf16_f32 v205, v148, v144
	s_setprio 1
	ds_read_b64_tr_b16 v[222:223], v85 offset:39424
	ds_read_b64_tr_b16 v[220:221], v85 offset:36864
	ds_read_b64_tr_b16 v[224:225], v85 offset:36896
	ds_read_b64_tr_b16 v[226:227], v85 offset:39456
	ds_read_b64_tr_b16 v[228:229], v85 offset:41984
	ds_read_b64_tr_b16 v[230:231], v85 offset:44544
	ds_read_b64_tr_b16 v[232:233], v85 offset:42016
	ds_read_b64_tr_b16 v[234:235], v85 offset:44576
	ds_read_b64_tr_b16 v[236:237], v85 offset:36928
	ds_read_b64_tr_b16 v[238:239], v85 offset:39488
	ds_read_b64_tr_b16 v[240:241], v85 offset:42048
	ds_read_b64_tr_b16 v[242:243], v85 offset:44608
	ds_read_b64_tr_b16 v[244:245], v85 offset:36960
	ds_read_b64_tr_b16 v[246:247], v85 offset:39520
	ds_read_b64_tr_b16 v[248:249], v85 offset:42080
	ds_read_b64_tr_b16 v[250:251], v85 offset:44640
	s_waitcnt lgkmcnt(14)
	v_mfma_f32_16x16x32_bf16 v[68:71], v[220:223], v[198:201], v[68:71]
	v_mfma_f32_16x16x32_bf16 v[52:55], v[220:223], v[194:197], v[52:55]
	s_waitcnt lgkmcnt(10)
	v_mfma_f32_16x16x32_bf16 v[68:71], v[228:231], v[76:79], v[68:71]
	v_mfma_f32_16x16x32_bf16 v[52:55], v[228:231], v[202:205], v[52:55]
	v_mfma_f32_16x16x32_bf16 v[64:67], v[224:227], v[198:201], v[64:67]
	v_mfma_f32_16x16x32_bf16 v[48:51], v[224:227], v[194:197], v[48:51]
	s_waitcnt lgkmcnt(8)
	v_mfma_f32_16x16x32_bf16 v[64:67], v[232:235], v[76:79], v[64:67]
	v_mfma_f32_16x16x32_bf16 v[48:51], v[232:235], v[202:205], v[48:51]
	s_waitcnt lgkmcnt(6)
	v_mfma_f32_16x16x32_bf16 v[72:75], v[236:239], v[198:201], v[72:75]
	v_mfma_f32_16x16x32_bf16 v[56:59], v[236:239], v[194:197], v[56:59]
	s_waitcnt lgkmcnt(4)
	v_mfma_f32_16x16x32_bf16 v[72:75], v[240:243], v[76:79], v[72:75]
	v_mfma_f32_16x16x32_bf16 v[56:59], v[240:243], v[202:205], v[56:59]
	s_waitcnt lgkmcnt(2)
	v_mfma_f32_16x16x32_bf16 v[60:63], v[244:247], v[194:197], v[60:63]
	v_mfma_f32_16x16x32_bf16 v[190:193], v[244:247], v[198:201], v[190:193]
	s_waitcnt lgkmcnt(0)
	v_mfma_f32_16x16x32_bf16 v[76:79], v[248:251], v[76:79], v[190:193]
	v_mfma_f32_16x16x32_bf16 v[60:63], v[248:251], v[202:205], v[60:63]
	s_nop 3
	s_setprio 0
	s_add_i32 s22, s10, 1
	s_cmp_ge_u32 s22, s19
	s_cbranch_scc1 .LBB0_2970
	s_bitcmp1_b32 s22, 0
	s_cselect_b32 s11, 0xb800, 0
	v_add3_u32 v85, s11, v95, v96
	s_waitcnt vmcnt(0)
	ds_write_b128 v85, v[28:31]
	v_add3_u32 v85, s11, v99, v96
	ds_write_b128 v85, v[36:39]
	v_add3_u32 v85, s11, v184, v96
	ds_write_b128 v85, v[32:35] offset:26624
	v_add3_u32 v85, s11, v185, v96
	ds_write_b128 v85, v[40:43] offset:26624
	v_add3_u32 v85, s11, v111, v98
	ds_write_b128 v85, v[44:47] offset:128

.LBB0_3345:
	flat_load_dword v4, v[0:1] sc1
	s_waitcnt vmcnt(0) lgkmcnt(0)
	v_readfirstlane_b32 s14, v4
	s_cmp_lt_u32 s14, 64
	s_cselect_b64 s[18:19], -1, 0
	s_and_b64 vcc, exec, s[18:19]
	s_cbranch_vccnz .LBB0_3347
.LBB0_3347:
	s_mov_b64 s[14:15], -1
	s_andn2_b64 vcc, exec, s[18:19]
	s_mov_b64 s[18:19], -1
	s_cbranch_vccnz .LBB0_3344
	s_and_b32 s14, s20, 0xff
	s_cmp_lg_u32 s14, 0
	s_cselect_b64 s[18:19], -1, 0
	s_cmp_eq_u32 s14, 0
	s_cbranch_scc1 .LBB0_3350
	s_mov_b64 s[14:15], -1
	s_andn2_b64 vcc, exec, s[18:19]
	s_mov_b64 s[18:19], -1
	s_cbranch_vccnz .LBB0_3344
	s_branch .LBB0_3351

.LBB0_3374:
	v_mov_b64_e32 v[144:145], s[50:51]
	s_waitcnt vmcnt(0)
	flat_load_dword v144, v[144:145] sc1
	s_waitcnt vmcnt(0) lgkmcnt(0)
	v_readfirstlane_b32 s66, v144
	s_cmp_lt_u32 s66, 64
	s_cselect_b64 s[68:69], -1, 0
	s_and_b64 vcc, exec, s[68:69]
	s_cbranch_vccnz .LBB0_3376
.LBB0_3376:
	s_mov_b64 s[66:67], -1
	s_andn2_b64 vcc, exec, s[68:69]
	s_mov_b64 s[68:69], -1
	s_cbranch_vccnz .LBB0_3373
	s_and_b32 s66, s20, 0xff
	s_cmp_lg_u32 s66, 0
	s_cselect_b64 s[68:69], -1, 0
	s_cmp_eq_u32 s66, 0
	s_cbranch_scc1 .LBB0_3379
	s_mov_b64 s[66:67], -1
	s_andn2_b64 vcc, exec, s[68:69]
	s_mov_b64 s[68:69], -1
	s_cbranch_vccnz .LBB0_3373
	s_branch .LBB0_3380
